# baseline (speedup 1.0000x reference)
; #define SLOAD(k0) do { sv0 = *reinterpret_cast<const bf16x8*>(Vp + (k0) * LDV); sv1 = *reinterpret_cast<const bf16x8*>(Vp + ((k0) + 32) * LDV); \
;     sk0 = *reinterpret_cast<const bf16x8*>(Kp + (k0) * LDK); sk1 = *reinterpret_cast<const bf16x8*>(Kp + ((k0) + 32) * LDK); \
;     if constexpr (DQK == 192) sk2 = *reinterpret_cast<const bf16x8*>(Kp2 + (k0) * LDK); } while (0)
; #define SWRITE(KB, VB) do { *(bf16x8*)(V_lds + (VB) * SHM_V + vst0) = sv0; *(bf16x8*)(V_lds + (VB) * SHM_V + vst1) = sv1; \
;     *(bf16x8*)(K_lds + (KB) * SHM_K + kst0) = sk0; *(bf16x8*)(K_lds + (KB) * SHM_K + kst1) = sk1; } while (0)
; #define SLOAD(TILE) do { sv = *reinterpret_cast<const u32x4*>(Vp + (TILE) * 8192); sk0 = *reinterpret_cast<const u32x4*>(Kp0 + (TILE) * (64 * 3072)); \
;     if (two) sk1 = *reinterpret_cast<const u32x4*>(Kp1 + (TILE) * (64 * 3072)); } while (0)
; #define SWRITE(KB, VB) do { *(u32x4*)(V_lds + (VB) * SHM_V8 + vst) = sv; *(u32x4*)(K_lds + (KB) * SHM_K8 + kst0) = sk0; \
;     if (two) *(u32x4*)(K_lds + (KB) * SHM_K8 + kst1) = sk1; } while (0)
; __device__ __forceinline__ void attn_body8(const bf16* __restrict__ Qb, const unsigned char* __restrict__ Kg, const unsigned char* __restrict__ Vg, ...
;     ...
;     __syncthreads();
;     if (j + 2 < NT) SWRITE((k4 + 2) & 3, VP2());
;     if (j + 3 < NT) SLOAD(j + 3);
.LBB0_906:
	s_cmp_gt_i32 s21, 2
	s_cselect_b32 s2, -3, 2
	s_add_i32 s2, s2, s21
	s_mulk_i32 s2, 0x2800
	s_xor_b32 s19, s22, 2
	v_add_u32_e32 v80, s2, v161
	s_mul_i32 s2, s19, 0x3400
	s_add_i32 s20, s2, 0
	s_waitcnt vmcnt(0)
	s_barrier
	ds_write_b128 v80, v[150:153]
	v_add_u32_e32 v80, s20, v158
	ds_write_b128 v80, v[154:157] offset:51200
	s_and_saveexec_b64 s[10:11], s[6:7]
	v_add_u32_e32 v80, s20, v160
	ds_write_b128 v80, v[146:149] offset:51200
	s_or_b64 exec, exec, s[10:11]
	s_cmpk_lt_u32 s18, 0xfd
	s_cselect_b64 s[14:15], -1, 0
	s_cmpk_gt_u32 s18, 0xfc
	s_cselect_b64 s[12:13], -1, 0
	s_and_b64 vcc, exec, s[12:13]
	s_cbranch_vccnz .LBB0_912
	global_load_dwordx4 v[150:153], v166, s[98:99]
	global_load_dwordx4 v[154:157], v252, s[100:101]
	s_and_saveexec_b64 s[10:11], s[6:7]
	s_cbranch_execz .LBB0_911
	global_load_dwordx4 v[146:149], v253, s[100:101]
